# latent Hyena K loop: shared-B LDS reads issued one iteration ahead (staging registers + moves)
# baseline (speedup 1.0000x reference)
; DI void hyena_item_lat(const Params& p, int l, int it) {
;     ...
;   const int c = it >> 2, f = l, L = 2048, posoff = CTXL;
;   const int tt0 = (it & 3) * 512 + w * 128;
;   const u16* R0 = WSP(const u16, OFF_RF) + ((size_t)(f * 256 + c) * 2) * RSTR;
;   const u16* R1 = R0 + RSTR;
;   const u16* UT = WSP(const u16, OFF_UT);
;   const int l16 = lane & 15, kg = lane >> 4;
;   f32x4 acc[8];
; #pragma unroll
;   for (int i = 0; i < 8; ++i) acc[i] = (f32x4){0.f, 0.f, 0.f, 0.f};
;   const u16* ub = UT + ((size_t)(c * 16 + l16)) * TPB + posoff + kg * 8;
;   const u16* rsel = (l16 & 1) ? (R1 - 1) : R0;
;   const int nb = L - (tt0 + l16) + kg * 8;
;   union AF { u32 u[4]; bf16x8 v; };
;   AF a[8];
;     ...
; #pragma unroll
;   for (int i = 2; i < 8; ++i) HY_LOADA(a[i], nb - 16 * i)
; #pragma unroll 1
;   for (int sb = 0; sb < L; sb += 128) {
; #pragma unroll
;     for (int u = 0; u < 4; ++u) {
;       const int s0 = sb + 32 * u;
;       HY_LOADA(a[(0 - 2 * u) & 7], nb + s0)
;       HY_LOADA(a[(1 - 2 * u) & 7], nb - 16 + s0)
;       const bf16x8 bfrag = *(const bf16x8*)(ub + s0);
; #pragma unroll
;       for (int i = 0; i < 8; ++i) acc[i] = __builtin_amdgcn_mfma_f32_16x16x32_bf16(a[(i - 2 * u) & 7].v, bfrag, acc[i], 0, 0, 0);
;     }
;   }
.LBB0_1137:
	s_andn2_b64 vcc, exec, s[34:35]
	s_cbranch_vccnz .LBB0_1141
	s_ashr_i32 s34, s13, 2
	v_mov_b32_e32 v0, v218
	v_mov_b32_e32 v1, v218
	s_add_i32 s36, s34, s42
	s_lshl_b32 s13, s13, 9
	s_ashr_i32 s37, s36, 31
	s_mul_i32 s38, s36, 0x4040
	v_readlane_b32 s16, v254, 47
	v_lshlrev_b32_e32 v1, 1, v1
	s_mul_hi_i32 s35, s36, 0x4040
	v_readlane_b32 s17, v254, 48
	s_add_u32 s38, s16, s38
	v_and_b32_e32 v1, 0xffffff80, v1
	s_addc_u32 s39, s17, s35
	s_and_b32 s13, s13, 0x600
	v_add_u32_e32 v63, s13, v1
	v_and_b32_e32 v62, 15, v0
	v_bfe_u32 v64, v0, 4, 2
	v_bfe_i32 v0, v0, 0, 1
	v_lshlrev_b32_e32 v1, 3, v64
	v_and_b32_e32 v172, 0x201e, v0
	v_or_b32_e32 v0, v63, v62
	v_sub_u32_e32 v58, v1, v0
	v_lshl_add_u64 v[56:57], s[38:39], 0, v[172:173]
	v_ashrrev_i32_e32 v59, 31, v58
	v_lshl_add_u64 v[0:1], v[58:59], 1, v[56:57]
	global_load_dwordx4 v[40:43], v[0:1], off offset:4032
	global_load_dwordx4 v[44:47], v[0:1], off offset:4000
	global_load_dwordx4 v[32:35], v[0:1], off offset:3968
	global_load_dwordx4 v[36:39], v[0:1], off offset:3936
	global_load_dwordx4 v[48:51], v[0:1], off offset:3904
	global_load_dwordx4 v[52:55], v[0:1], off offset:3872
	s_lshl_b32 s35, s34, 4
	v_or_b32_e32 v59, s35, v62
	v_mad_i64_i32 v[0:1], s[38:39], v59, s9, 0
	v_readlane_b32 s16, v255, 56
	v_lshl_or_b32 v0, v64, 4, v0
	v_readlane_b32 s17, v255, 57
	v_mov_b32_e32 v28, 0
	s_mov_b64 s[46:47], s[20:21]
	s_movk_i32 s13, 0xff80
	v_lshl_add_u64 v[60:61], s[16:17], 0, v[0:1]
	v_mov_b32_e32 v29, v28
	v_mov_b32_e32 v30, v28
	v_mov_b32_e32 v31, v28
	v_mov_b32_e32 v24, v28
	v_mov_b32_e32 v25, v28
	v_mov_b32_e32 v26, v28
	v_mov_b32_e32 v27, v28
	v_mov_b32_e32 v20, v28
	v_mov_b32_e32 v21, v28
	v_mov_b32_e32 v22, v28
	v_mov_b32_e32 v23, v28
	v_mov_b32_e32 v16, v28
	v_mov_b32_e32 v17, v28
	v_mov_b32_e32 v18, v28
	v_mov_b32_e32 v19, v28
	v_mov_b32_e32 v12, v28
	v_mov_b32_e32 v13, v28
	v_mov_b32_e32 v14, v28
	v_mov_b32_e32 v15, v28
	v_mov_b32_e32 v8, v28
	v_mov_b32_e32 v9, v28
	v_mov_b32_e32 v10, v28
	v_mov_b32_e32 v11, v28
	v_mov_b32_e32 v4, v28
	v_mov_b32_e32 v5, v28
	v_mov_b32_e32 v6, v28
	v_mov_b32_e32 v7, v28
	v_mov_b32_e32 v0, v28
	v_mov_b32_e32 v1, v28
	v_mov_b32_e32 v2, v28
	v_mov_b32_e32 v3, v28
	v_and_b32_e32 v92, 0xc0, v218
	v_mov_b32_e32 v93, 0
	v_lshlrev_b32_e32 v94, 4, v218
	v_and_b32_e32 v95, 63, v218
	v_lshl_add_u64 v[90:91], v[92:93], 0, v[60:61]
	v_lshlrev_b32_e32 v95, 4, v95
	global_load_dwordx4 v[82:85], v[90:91], off offset:-192
	s_waitcnt vmcnt(0)
	ds_write_b128 v94, v[82:85]
	global_load_dwordx4 v[82:85], v[90:91], off offset:64
	s_waitcnt lgkmcnt(0)
	s_barrier
	ds_read_b128 v[104:107], v95
	ds_read_b128 v[108:111], v95 offset:1024
	ds_read_b128 v[120:123], v95 offset:2048
	ds_read_b128 v[124:127], v95 offset:3072
	v_xor_b32_e32 v94, 0x1000, v94
	v_xor_b32_e32 v95, 0x1000, v95
.LBB0_1139:
	s_waitcnt vmcnt(0) lgkmcnt(0)
	v_mov_b64_e32 v[66:67], v[104:105]
	v_mov_b64_e32 v[68:69], v[106:107]
	v_mov_b64_e32 v[70:71], v[108:109]
	v_mov_b64_e32 v[72:73], v[110:111]
	v_mov_b64_e32 v[86:87], v[120:121]
	v_mov_b64_e32 v[88:89], v[122:123]
	v_mov_b64_e32 v[74:75], v[124:125]
	v_mov_b64_e32 v[76:77], v[126:127]
	ds_write_b128 v94, v[82:85]
	s_waitcnt lgkmcnt(0)
	s_barrier
	ds_read_b128 v[104:107], v95
	ds_read_b128 v[108:111], v95 offset:1024
	ds_read_b128 v[120:123], v95 offset:2048
	ds_read_b128 v[124:127], v95 offset:3072
	v_xor_b32_e32 v94, 0x1000, v94
	v_xor_b32_e32 v95, 0x1000, v95
	s_mov_b64 s[38:39], 0x100
	v_mfma_f32_16x16x32_bf16 v[4:7], v[48:51], v[66:69], v[4:7]
	v_add_u32_e32 v49, s13, v58
	v_add_u32_e32 v48, 0x880, v49
	v_add_u32_e32 v50, 0x870, v49
	v_mfma_f32_16x16x32_bf16 v[0:3], v[52:55], v[66:69], v[0:3]
	v_ashrrev_i32_e32 v49, 31, v48
	v_ashrrev_i32_e32 v51, 31, v50
	v_lshl_add_u64 v[78:79], v[48:49], 1, v[56:57]
	v_lshl_add_u64 v[80:81], v[50:51], 1, v[56:57]
	v_mfma_f32_16x16x32_bf16 v[12:15], v[32:35], v[66:69], v[12:15]
	global_load_dwordx4 v[48:51], v[78:79], off offset:64
	global_load_dwordx4 v[52:55], v[80:81], off offset:64
	s_addk_i32 s13, 0x80
	v_mfma_f32_16x16x32_bf16 v[8:11], v[36:39], v[66:69], v[8:11]
	s_cmpk_lt_u32 s13, 0x780
	v_mfma_f32_16x16x32_bf16 v[4:7], v[32:35], v[70:73], v[4:7]
	global_load_dwordx4 v[32:35], v[78:79], off
	v_mfma_f32_16x16x32_bf16 v[0:3], v[36:39], v[70:73], v[0:3]
	global_load_dwordx4 v[36:39], v[80:81], off
	v_mfma_f32_16x16x32_bf16 v[20:23], v[40:43], v[66:69], v[20:23]
	v_mfma_f32_16x16x32_bf16 v[16:19], v[44:47], v[66:69], v[16:19]
	s_waitcnt vmcnt(1)
	v_mfma_f32_16x16x32_bf16 v[28:31], v[32:35], v[66:69], v[28:31]
	s_waitcnt vmcnt(0)
	v_mfma_f32_16x16x32_bf16 v[24:27], v[36:39], v[66:69], v[24:27]
	global_load_dwordx4 v[82:85], v[90:91], off offset:320
	v_lshl_add_u64 v[90:91], v[90:91], 0, s[38:39]
	v_lshl_add_u64 v[60:61], v[60:61], 0, s[38:39]
	v_mfma_f32_16x16x32_bf16 v[12:15], v[40:43], v[70:73], v[12:15]
	v_mfma_f32_16x16x32_bf16 v[8:11], v[44:47], v[70:73], v[8:11]
	v_mfma_f32_16x16x32_bf16 v[20:23], v[32:35], v[70:73], v[20:23]
	v_mfma_f32_16x16x32_bf16 v[16:19], v[36:39], v[70:73], v[16:19]
	v_mfma_f32_16x16x32_bf16 v[28:31], v[48:51], v[70:73], v[28:31]
	v_mfma_f32_16x16x32_bf16 v[24:27], v[52:55], v[70:73], v[24:27]
	v_mfma_f32_16x16x32_bf16 v[4:7], v[40:43], v[86:89], v[4:7]
	global_load_dwordx4 v[40:43], v[78:79], off offset:192
	v_mfma_f32_16x16x32_bf16 v[0:3], v[44:47], v[86:89], v[0:3]
	global_load_dwordx4 v[44:47], v[80:81], off offset:192
	v_mfma_f32_16x16x32_bf16 v[12:15], v[32:35], v[86:89], v[12:15]
	v_mfma_f32_16x16x32_bf16 v[8:11], v[36:39], v[86:89], v[8:11]
	v_mfma_f32_16x16x32_bf16 v[4:7], v[32:35], v[74:77], v[4:7]
	global_load_dwordx4 v[32:35], v[78:79], off offset:128
	v_mfma_f32_16x16x32_bf16 v[0:3], v[36:39], v[74:77], v[0:3]
	global_load_dwordx4 v[36:39], v[80:81], off offset:128
	v_mfma_f32_16x16x32_bf16 v[20:23], v[48:51], v[86:89], v[20:23]
	v_mfma_f32_16x16x32_bf16 v[16:19], v[52:55], v[86:89], v[16:19]
	v_mfma_f32_16x16x32_bf16 v[12:15], v[48:51], v[74:77], v[12:15]
	v_mfma_f32_16x16x32_bf16 v[8:11], v[52:55], v[74:77], v[8:11]
	s_waitcnt vmcnt(1)
	v_mfma_f32_16x16x32_bf16 v[28:31], v[32:35], v[86:89], v[28:31]
	s_waitcnt vmcnt(0)
	v_mfma_f32_16x16x32_bf16 v[24:27], v[36:39], v[86:89], v[24:27]
	v_mfma_f32_16x16x32_bf16 v[20:23], v[32:35], v[74:77], v[20:23]
	v_mfma_f32_16x16x32_bf16 v[16:19], v[36:39], v[74:77], v[16:19]
	v_mfma_f32_16x16x32_bf16 v[28:31], v[40:43], v[74:77], v[28:31]
	v_mfma_f32_16x16x32_bf16 v[24:27], v[44:47], v[74:77], v[24:27]
	s_cbranch_scc1 .LBB0_1139
; DI float bf2f(u16 v) { return __uint_as_float(((u32)v) << 16); }
; DI void hyena_item_lat(const Params& p, int l, int it) {
;     ...
;   float ssq = 0.f;
;   for (int t = 0; t < 32; ++t) ssq += WSP(const float, OFF_PART)[(size_t)(f * 32 + t) * 256 + c];
;   const float scale = rsqrtf(ssq + EPSF);
;   const float bias = p.in[I_HYBIAS][l * 256 + c];
;   const u16* X1C = WSP(const u16, OFF_X1C);
;   u16* YM = WSP(u16, OFF_ACT);
;   const int b = l16;
; #pragma unroll
;   for (int i = 0; i < 8; ++i)
; #pragma unroll
;     for (int r = 0; r < 4; ++r) {
;       const int t = tt0 + 16 * i + kg * 4 + r;
;       const size_t row = (size_t)b * TPB + posoff + t;
;       const float uu = bf2f(UT[((size_t)(c * 16 + b)) * TPB + posoff + t]);
	s_waitcnt vmcnt(0)
	v_mov_b64_e32 v[32:33], s[96:97]
	v_mad_i64_i32 v[32:33], s[38:39], v59, s9, v[32:33]
	s_mov_b64 s[38:39], 0x15600200
	s_ashr_i32 s35, s34, 31
	v_lshl_add_u64 v[32:33], v[32:33], 0, s[38:39]
	s_lshl_b64 s[38:39], s[34:35], 2
	s_add_u32 s38, s43, s38
	s_addc_u32 s39, s44, s39
	global_load_dword v38, v173, s[38:39]
	global_load_dword v39, v173, s[38:39] offset:1024
	global_load_dword v40, v173, s[38:39] offset:2048
	global_load_dword v41, v173, s[38:39] offset:3072
	v_mov_b32_e32 v92, 0x1000
	global_load_dword v42, v92, s[38:39]
	global_load_dword v43, v92, s[38:39] offset:1024
	global_load_dword v44, v92, s[38:39] offset:2048
	global_load_dword v45, v92, s[38:39] offset:3072
	v_mov_b32_e32 v92, 0x2000
	global_load_dword v46, v92, s[38:39]
	global_load_dword v47, v92, s[38:39] offset:1024
	global_load_dword v48, v92, s[38:39] offset:2048
	global_load_dword v49, v92, s[38:39] offset:3072
	v_mov_b32_e32 v92, 0x3000
	global_load_dword v50, v92, s[38:39]
	global_load_dword v51, v92, s[38:39] offset:1024
	global_load_dword v52, v92, s[38:39] offset:2048
	global_load_dword v53, v92, s[38:39] offset:3072
	v_mov_b32_e32 v92, 0x4000
	global_load_dword v54, v92, s[38:39]
	global_load_dword v55, v92, s[38:39] offset:1024
	global_load_dword v56, v92, s[38:39] offset:2048
	global_load_dword v57, v92, s[38:39] offset:3072
	v_mov_b32_e32 v92, 0x5000
	global_load_dword v58, v92, s[38:39]
	global_load_dword v65, v92, s[38:39] offset:1024
	global_load_dword v66, v92, s[38:39] offset:2048
	global_load_dword v67, v92, s[38:39] offset:3072
	v_mov_b32_e32 v92, 0x6000
	global_load_dword v68, v92, s[38:39]
	global_load_dword v69, v92, s[38:39] offset:1024
	global_load_dword v70, v92, s[38:39] offset:2048
	global_load_dword v71, v92, s[38:39] offset:3072
	v_mov_b32_e32 v92, 0x7000
	global_load_dword v72, v92, s[38:39]
	global_load_dword v73, v92, s[38:39] offset:1024
	global_load_dword v74, v92, s[38:39] offset:2048
	global_load_dword v75, v92, s[38:39] offset:3072
	v_readlane_b32 s16, v254, 29
	s_lshl_b64 s[36:37], s[36:37], 2
	v_readlane_b32 s18, v254, 31
	v_readlane_b32 s19, v254, 32
	s_add_u32 s36, s18, s36
	s_addc_u32 s37, s19, s37
	global_load_dword v37, v173, s[36:37]
	s_movk_i32 s13, 0x900
	v_lshl_or_b32 v34, v64, 2, v63
	v_mov_b32_e32 v35, 0x100
	v_mad_u32_u24 v172, v62, s13, v35
	v_mov_b32_e32 v35, 0
	v_lshl_add_u64 v[94:95], v[34:35], 1, v[32:33]
	global_load_dwordx2 v[76:77], v[94:95], off
	global_load_dwordx2 v[78:79], v[94:95], off offset:32
	global_load_dwordx2 v[80:81], v[94:95], off offset:64
	global_load_dwordx2 v[82:83], v[94:95], off offset:96
	global_load_dwordx2 v[84:85], v[94:95], off offset:128
	global_load_dwordx2 v[86:87], v[94:95], off offset:160
	global_load_dwordx2 v[88:89], v[94:95], off offset:192
	global_load_dwordx2 v[90:91], v[94:95], off offset:224
	v_readlane_b32 s17, v254, 30
	s_lshl_b64 s[34:35], s[34:35], 1
	v_readlane_b32 s16, v255, 42
	v_readlane_b32 s17, v255, 43
	v_readlane_b32 s20, v254, 33
	v_readlane_b32 s21, v254, 34
	v_readlane_b32 s24, v254, 37
	v_readlane_b32 s18, v254, 10
	s_mov_b64 s[20:21], s[46:47]
	s_mov_b32 s24, s64
	v_readlane_b32 s22, v254, 35
	v_readlane_b32 s23, v254, 36
	v_readlane_b32 s25, v254, 38
	v_readlane_b32 s26, v254, 39
	v_readlane_b32 s27, v254, 40
	v_readlane_b32 s28, v254, 41
	v_readlane_b32 s29, v254, 42
	v_readlane_b32 s30, v254, 43
	v_readlane_b32 s31, v254, 44
	v_readlane_b32 s19, v254, 11
	s_add_u32 s38, s16, s34
	s_addc_u32 s39, s17, s35
	s_add_u32 s36, s6, s34
	s_addc_u32 s37, s7, s35
	v_lshlrev_b32_e32 v142, 13, v62
	v_lshl_add_u32 v142, v34, 2, v142
	s_waitcnt vmcnt(0)
; DI u16 f2bf(float x) { u32 u = __float_as_uint(x); u += 0x7fffu + ((u >> 16) & 1u); return (u16)(u >> 16); }
; DI float bf2f(u16 v) { return __uint_as_float(((u32)v) << 16); }
; DI void hyena_item_lat(const Params& p, int l, int it) {
;     ...
;   float ssq = 0.f;
;   for (int t = 0; t < 32; ++t) ssq += WSP(const float, OFF_PART)[(size_t)(f * 32 + t) * 256 + c];
;   const float scale = rsqrtf(ssq + EPSF);
;   const float bias = p.in[I_HYBIAS][l * 256 + c];
;   const u16* X1C = WSP(const u16, OFF_X1C);
;   u16* YM = WSP(u16, OFF_ACT);
;   const int b = l16;
; #pragma unroll
;   for (int i = 0; i < 8; ++i)
; #pragma unroll
;     for (int r = 0; r < 4; ++r) {
;       const int t = tt0 + 16 * i + kg * 4 + r;
;       const size_t row = (size_t)b * TPB + posoff + t;
;       const float uu = bf2f(UT[((size_t)(c * 16 + b)) * TPB + posoff + t]);
;       const float x1 = bf2f(X1C[row * 256 + c]);
;       YM[row * 1024 + c] = f2bf(x1 * (scale * acc[i][r] + bias * uu));
;     }
	v_add_f32_e32 v36, 0, v38
	v_add_f32_e32 v36, v36, v39
	v_add_f32_e32 v36, v36, v40
	v_add_f32_e32 v36, v36, v41
	v_add_f32_e32 v36, v36, v42
	v_add_f32_e32 v36, v36, v43
	v_add_f32_e32 v36, v36, v44
	v_add_f32_e32 v36, v36, v45
	v_add_f32_e32 v36, v36, v46
	v_add_f32_e32 v36, v36, v47
	v_add_f32_e32 v36, v36, v48
	v_add_f32_e32 v36, v36, v49
	v_add_f32_e32 v36, v36, v50
	v_add_f32_e32 v36, v36, v51
	v_add_f32_e32 v36, v36, v52
	v_add_f32_e32 v36, v36, v53
	v_add_f32_e32 v36, v36, v54
	v_add_f32_e32 v36, v36, v55
	v_add_f32_e32 v36, v36, v56
	v_add_f32_e32 v36, v36, v57
	v_add_f32_e32 v36, v36, v58
	v_add_f32_e32 v36, v36, v65
	v_add_f32_e32 v36, v36, v66
	v_add_f32_e32 v36, v36, v67
	v_add_f32_e32 v36, v36, v68
	v_add_f32_e32 v36, v36, v69
	v_add_f32_e32 v36, v36, v70
	v_add_f32_e32 v36, v36, v71
	v_add_f32_e32 v36, v36, v72
	v_add_f32_e32 v36, v36, v73
	v_add_f32_e32 v36, v36, v74
	v_add_f32_e32 v36, v36, v75
	s_mov_b32 s13, 0x800000
	v_add_f32_e32 v36, 0x358637bd, v36
	v_cmp_gt_f32_e32 vcc, s13, v36
	v_mul_f32_e32 v35, 0x4b800000, v36
	s_movk_i32 s13, 0x900
	s_nop 0
	v_cndmask_b32_e32 v36, v36, v35, vcc
	v_rsq_f32_e32 v36, v36
	s_nop 0
	v_mul_f32_e32 v35, 0x45800000, v36
	v_cndmask_b32_e32 v36, v36, v35, vcc
	v_lshlrev_b32_e32 v92, 16, v76
	v_mul_f32_e32 v92, v37, v92
	v_fmac_f32_e32 v92, v28, v36
	v_mov_b32_e32 v28, v92
	v_and_b32_e32 v92, 0xffff0000, v76
	v_mul_f32_e32 v92, v37, v92
	v_fmac_f32_e32 v92, v29, v36
	v_mov_b32_e32 v29, v92
	v_lshlrev_b32_e32 v92, 16, v77
	v_mul_f32_e32 v92, v37, v92
	v_fmac_f32_e32 v92, v30, v36
	v_mov_b32_e32 v30, v92
	v_and_b32_e32 v92, 0xffff0000, v77
	v_mul_f32_e32 v92, v37, v92
	v_fmac_f32_e32 v92, v31, v36
	v_mov_b32_e32 v31, v92
	v_lshlrev_b32_e32 v92, 16, v78
	v_mul_f32_e32 v92, v37, v92
	v_fmac_f32_e32 v92, v24, v36
	v_mov_b32_e32 v24, v92
	v_and_b32_e32 v92, 0xffff0000, v78
	v_mul_f32_e32 v92, v37, v92
	v_fmac_f32_e32 v92, v25, v36
	v_mov_b32_e32 v25, v92
	v_lshlrev_b32_e32 v92, 16, v79
	v_mul_f32_e32 v92, v37, v92
	v_fmac_f32_e32 v92, v26, v36
	v_mov_b32_e32 v26, v92
	v_and_b32_e32 v92, 0xffff0000, v79
	v_mul_f32_e32 v92, v37, v92
	v_fmac_f32_e32 v92, v27, v36
	v_mov_b32_e32 v27, v92
	v_lshlrev_b32_e32 v92, 16, v80
	v_mul_f32_e32 v92, v37, v92
	v_fmac_f32_e32 v92, v20, v36
	v_mov_b32_e32 v20, v92
	v_and_b32_e32 v92, 0xffff0000, v80
	v_mul_f32_e32 v92, v37, v92
	v_fmac_f32_e32 v92, v21, v36
	v_mov_b32_e32 v21, v92
	v_lshlrev_b32_e32 v92, 16, v81
	v_mul_f32_e32 v92, v37, v92
	v_fmac_f32_e32 v92, v22, v36
	v_mov_b32_e32 v22, v92
	v_and_b32_e32 v92, 0xffff0000, v81
	v_mul_f32_e32 v92, v37, v92
	v_fmac_f32_e32 v92, v23, v36
	v_mov_b32_e32 v23, v92
	v_lshlrev_b32_e32 v92, 16, v82
	v_mul_f32_e32 v92, v37, v92
	v_fmac_f32_e32 v92, v16, v36
	v_mov_b32_e32 v16, v92
	v_and_b32_e32 v92, 0xffff0000, v82
	v_mul_f32_e32 v92, v37, v92
	v_fmac_f32_e32 v92, v17, v36
	v_mov_b32_e32 v17, v92
	v_lshlrev_b32_e32 v92, 16, v83
	v_mul_f32_e32 v92, v37, v92
	v_fmac_f32_e32 v92, v18, v36
	v_mov_b32_e32 v18, v92
	v_and_b32_e32 v92, 0xffff0000, v83
	v_mul_f32_e32 v92, v37, v92
	v_fmac_f32_e32 v92, v19, v36
	v_mov_b32_e32 v19, v92
	v_lshlrev_b32_e32 v92, 16, v84
	v_mul_f32_e32 v92, v37, v92
	v_fmac_f32_e32 v92, v12, v36
	v_mov_b32_e32 v12, v92
	v_and_b32_e32 v92, 0xffff0000, v84
	v_mul_f32_e32 v92, v37, v92
	v_fmac_f32_e32 v92, v13, v36
	v_mov_b32_e32 v13, v92
	v_lshlrev_b32_e32 v92, 16, v85
	v_mul_f32_e32 v92, v37, v92
	v_fmac_f32_e32 v92, v14, v36
	v_mov_b32_e32 v14, v92
	v_and_b32_e32 v92, 0xffff0000, v85
	v_mul_f32_e32 v92, v37, v92
	v_fmac_f32_e32 v92, v15, v36
	v_mov_b32_e32 v15, v92
	v_lshlrev_b32_e32 v92, 16, v86
	v_mul_f32_e32 v92, v37, v92
	v_fmac_f32_e32 v92, v8, v36
	v_mov_b32_e32 v8, v92
	v_and_b32_e32 v92, 0xffff0000, v86
	v_mul_f32_e32 v92, v37, v92
	v_fmac_f32_e32 v92, v9, v36
	v_mov_b32_e32 v9, v92
	v_lshlrev_b32_e32 v92, 16, v87
	v_mul_f32_e32 v92, v37, v92
	v_fmac_f32_e32 v92, v10, v36
	v_mov_b32_e32 v10, v92
	v_and_b32_e32 v92, 0xffff0000, v87
	v_mul_f32_e32 v92, v37, v92
	v_fmac_f32_e32 v92, v11, v36
	v_mov_b32_e32 v11, v92
	v_lshlrev_b32_e32 v92, 16, v88
	v_mul_f32_e32 v92, v37, v92
	v_fmac_f32_e32 v92, v4, v36
	v_mov_b32_e32 v4, v92
	v_and_b32_e32 v92, 0xffff0000, v88
	v_mul_f32_e32 v92, v37, v92
	v_fmac_f32_e32 v92, v5, v36
	v_mov_b32_e32 v5, v92
	v_lshlrev_b32_e32 v92, 16, v89
	v_mul_f32_e32 v92, v37, v92
	v_fmac_f32_e32 v92, v6, v36
	v_mov_b32_e32 v6, v92
	v_and_b32_e32 v92, 0xffff0000, v89
	v_mul_f32_e32 v92, v37, v92
	v_fmac_f32_e32 v92, v7, v36
	v_mov_b32_e32 v7, v92
	v_lshlrev_b32_e32 v92, 16, v90
	v_mul_f32_e32 v92, v37, v92
	v_fmac_f32_e32 v92, v0, v36
	v_mov_b32_e32 v0, v92
	v_and_b32_e32 v92, 0xffff0000, v90
	v_mul_f32_e32 v92, v37, v92
	v_fmac_f32_e32 v92, v1, v36
	v_mov_b32_e32 v1, v92
	v_lshlrev_b32_e32 v92, 16, v91
	v_mul_f32_e32 v92, v37, v92
	v_fmac_f32_e32 v92, v2, v36
	v_mov_b32_e32 v2, v92
	v_and_b32_e32 v92, 0xffff0000, v91
	v_mul_f32_e32 v92, v37, v92
	v_fmac_f32_e32 v92, v3, v36
	v_mov_b32_e32 v3, v92
	s_lshl_b32 s38, s34, 16
	s_add_u32 s38, s96, s38
	s_addc_u32 s39, s97, 0
	global_store_dwordx4 v142, v[28:31], s[38:39]
	global_store_dwordx4 v142, v[24:27], s[38:39] offset:64
	global_store_dwordx4 v142, v[20:23], s[38:39] offset:128
	global_store_dwordx4 v142, v[16:19], s[38:39] offset:192
	global_store_dwordx4 v142, v[12:15], s[38:39] offset:256
	global_store_dwordx4 v142, v[8:11], s[38:39] offset:320
	global_store_dwordx4 v142, v[4:7], s[38:39] offset:384
	global_store_dwordx4 v142, v[0:3], s[38:39] offset:448
